# prep GEMM jobs: RMS-norm prologue loads issued together (16/8 loads) behind counted waits instead of one full wait per 16-byte load
# baseline (speedup 1.0000x reference)
.LBB0_725:
	s_andn2_b64 vcc, exec, s[0:1]
	s_cbranch_vccnz .LBB0_737
	v_readlane_b32 s0, v254, 45
	s_add_i32 s8, s0, 0xfffffe40
	s_lshl_b32 s0, s8, 7
	s_and_b32 s10, s0, 0x3f80
	v_readlane_b32 s0, v254, 25
	v_ashrrev_i32_e32 v2, 1, v198
	v_readlane_b32 s1, v254, 26
	v_and_b32_e32 v3, 1, v198
	v_add_u32_e32 v4, s10, v2
	v_mov_b64_e32 v[0:1], s[0:1]
	v_mad_i64_i32 v[0:1], s[0:1], v4, s16, v[0:1]
	v_lshlrev_b32_e32 v192, 7, v3
	v_lshl_add_u64 v[0:1], v[0:1], 0, v[192:193]
	s_waitcnt lgkmcnt(0)
	s_barrier
	global_load_dwordx4 v[64:67], v[0:1], off
	global_load_dwordx4 v[68:71], v[0:1], off offset:16
	global_load_dwordx4 v[72:75], v[0:1], off offset:32
	global_load_dwordx4 v[76:79], v[0:1], off offset:48
	global_load_dwordx4 v[80:83], v[0:1], off offset:64
	global_load_dwordx4 v[84:87], v[0:1], off offset:80
	global_load_dwordx4 v[88:91], v[0:1], off offset:96
	global_load_dwordx4 v[92:95], v[0:1], off offset:112
	v_and_b32_e32 v1, 64, v225
	v_add_u32_e32 v1, 64, v1
	s_waitcnt vmcnt(7)
	v_lshlrev_b32_e32 v5, 16, v64
	v_mul_f32_e32 v4, v5, v5
	v_and_b32_e32 v5, 0xffff0000, v64
	v_fmac_f32_e32 v4, v5, v5
	v_lshlrev_b32_e32 v5, 16, v65
	v_fmac_f32_e32 v4, v5, v5
	v_and_b32_e32 v5, 0xffff0000, v65
	v_fmac_f32_e32 v4, v5, v5
	v_lshlrev_b32_e32 v5, 16, v66
	v_fmac_f32_e32 v4, v5, v5
	v_and_b32_e32 v5, 0xffff0000, v66
	v_fmac_f32_e32 v4, v5, v5
	v_lshlrev_b32_e32 v5, 16, v67
	v_fmac_f32_e32 v4, v5, v5
	v_and_b32_e32 v5, 0xffff0000, v67
	v_fmac_f32_e32 v4, v5, v5
	s_waitcnt vmcnt(6)
	v_lshlrev_b32_e32 v5, 16, v68
	v_fmac_f32_e32 v4, v5, v5
	v_and_b32_e32 v5, 0xffff0000, v68
	v_fmac_f32_e32 v4, v5, v5
	v_lshlrev_b32_e32 v5, 16, v69
	v_fmac_f32_e32 v4, v5, v5
	v_and_b32_e32 v5, 0xffff0000, v69
	v_fmac_f32_e32 v4, v5, v5
	v_lshlrev_b32_e32 v5, 16, v70
	v_fmac_f32_e32 v4, v5, v5
	v_and_b32_e32 v5, 0xffff0000, v70
	v_fmac_f32_e32 v4, v5, v5
	v_lshlrev_b32_e32 v5, 16, v71
	v_fmac_f32_e32 v4, v5, v5
	v_and_b32_e32 v5, 0xffff0000, v71
	v_fmac_f32_e32 v4, v5, v5
	s_waitcnt vmcnt(5)
	v_lshlrev_b32_e32 v5, 16, v72
	v_fmac_f32_e32 v4, v5, v5
	v_and_b32_e32 v5, 0xffff0000, v72
	v_fmac_f32_e32 v4, v5, v5
	v_lshlrev_b32_e32 v5, 16, v73
	v_fmac_f32_e32 v4, v5, v5
	v_and_b32_e32 v5, 0xffff0000, v73
	v_fmac_f32_e32 v4, v5, v5
	v_lshlrev_b32_e32 v5, 16, v74
	v_fmac_f32_e32 v4, v5, v5
	v_and_b32_e32 v5, 0xffff0000, v74
	v_fmac_f32_e32 v4, v5, v5
	v_lshlrev_b32_e32 v5, 16, v75
	v_fmac_f32_e32 v4, v5, v5
	v_and_b32_e32 v5, 0xffff0000, v75
	v_fmac_f32_e32 v4, v5, v5
	s_waitcnt vmcnt(4)
	v_lshlrev_b32_e32 v5, 16, v76
	v_fmac_f32_e32 v4, v5, v5
	v_and_b32_e32 v5, 0xffff0000, v76
	v_fmac_f32_e32 v4, v5, v5
	v_lshlrev_b32_e32 v5, 16, v77
	v_fmac_f32_e32 v4, v5, v5
	v_and_b32_e32 v5, 0xffff0000, v77
	v_fmac_f32_e32 v4, v5, v5
	v_lshlrev_b32_e32 v5, 16, v78
	v_fmac_f32_e32 v4, v5, v5
	v_and_b32_e32 v5, 0xffff0000, v78
	v_fmac_f32_e32 v4, v5, v5
	v_lshlrev_b32_e32 v5, 16, v79
	v_fmac_f32_e32 v4, v5, v5
	v_and_b32_e32 v5, 0xffff0000, v79
	v_fmac_f32_e32 v4, v5, v5
	s_waitcnt vmcnt(3)
	v_lshlrev_b32_e32 v5, 16, v80
	v_fmac_f32_e32 v4, v5, v5
	v_and_b32_e32 v5, 0xffff0000, v80
	v_fmac_f32_e32 v4, v5, v5
	v_lshlrev_b32_e32 v5, 16, v81
	v_fmac_f32_e32 v4, v5, v5
	v_and_b32_e32 v5, 0xffff0000, v81
	v_fmac_f32_e32 v4, v5, v5
	v_lshlrev_b32_e32 v5, 16, v82
	v_fmac_f32_e32 v4, v5, v5
	v_and_b32_e32 v5, 0xffff0000, v82
	v_fmac_f32_e32 v4, v5, v5
	v_lshlrev_b32_e32 v5, 16, v83
	v_fmac_f32_e32 v4, v5, v5
	v_and_b32_e32 v5, 0xffff0000, v83
	v_fmac_f32_e32 v4, v5, v5
	s_waitcnt vmcnt(2)
	v_lshlrev_b32_e32 v5, 16, v84
	v_fmac_f32_e32 v4, v5, v5
	v_and_b32_e32 v5, 0xffff0000, v84
	v_fmac_f32_e32 v4, v5, v5
	v_lshlrev_b32_e32 v5, 16, v85
	v_fmac_f32_e32 v4, v5, v5
	v_and_b32_e32 v5, 0xffff0000, v85
	v_fmac_f32_e32 v4, v5, v5
	v_lshlrev_b32_e32 v5, 16, v86
	v_fmac_f32_e32 v4, v5, v5
	v_and_b32_e32 v5, 0xffff0000, v86
	v_fmac_f32_e32 v4, v5, v5
	v_lshlrev_b32_e32 v5, 16, v87
	v_fmac_f32_e32 v4, v5, v5
	v_and_b32_e32 v5, 0xffff0000, v87
	v_fmac_f32_e32 v4, v5, v5
	s_waitcnt vmcnt(1)
	v_lshlrev_b32_e32 v5, 16, v88
	v_fmac_f32_e32 v4, v5, v5
	v_and_b32_e32 v5, 0xffff0000, v88
	v_fmac_f32_e32 v4, v5, v5
	v_lshlrev_b32_e32 v5, 16, v89
	v_fmac_f32_e32 v4, v5, v5
	v_and_b32_e32 v5, 0xffff0000, v89
	v_fmac_f32_e32 v4, v5, v5
	v_lshlrev_b32_e32 v5, 16, v90
	v_fmac_f32_e32 v4, v5, v5
	v_and_b32_e32 v5, 0xffff0000, v90
	v_fmac_f32_e32 v4, v5, v5
	v_lshlrev_b32_e32 v5, 16, v91
	v_fmac_f32_e32 v4, v5, v5
	v_and_b32_e32 v5, 0xffff0000, v91
	v_fmac_f32_e32 v4, v5, v5
	s_waitcnt vmcnt(0)
	v_lshlrev_b32_e32 v5, 16, v92
	v_fmac_f32_e32 v4, v5, v5
	v_and_b32_e32 v5, 0xffff0000, v92
	v_fmac_f32_e32 v4, v5, v5
	v_lshlrev_b32_e32 v5, 16, v93
	v_fmac_f32_e32 v4, v5, v5
	v_and_b32_e32 v5, 0xffff0000, v93
	v_fmac_f32_e32 v4, v5, v5
	v_lshlrev_b32_e32 v5, 16, v94
	v_fmac_f32_e32 v4, v5, v5
	v_and_b32_e32 v5, 0xffff0000, v94
	v_fmac_f32_e32 v4, v5, v5
	v_lshlrev_b32_e32 v5, 16, v95
	v_fmac_f32_e32 v4, v5, v5
	v_and_b32_e32 v5, 0xffff0000, v95
	v_fmac_f32_e32 v4, v5, v5
	v_xor_b32_e32 v0, 1, v225
	v_cmp_lt_i32_e32 vcc, v0, v1
	s_nop 1
	v_cndmask_b32_e32 v0, v225, v0, vcc
	v_lshlrev_b32_e32 v0, 2, v0
	ds_bpermute_b32 v0, v0, v4
	v_cmp_eq_u32_e32 vcc, 0, v3
	s_and_saveexec_b64 s[0:1], vcc
	s_movk_i32 s9, 0x90
	s_cbranch_execz .LBB0_728
	s_waitcnt lgkmcnt(0)
	v_add_f32_e32 v0, v4, v0
	v_fmamk_f32 v0, v0, 0x3c000000, v224
	s_mov_b32 s11, 0x800000
	v_mul_f32_e32 v1, 0x4b800000, v0
	v_cmp_gt_f32_e32 vcc, s11, v0
	s_nop 1
	v_cndmask_b32_e32 v0, v0, v1, vcc
	v_rsq_f32_e32 v0, v0
	s_nop 0
	v_mul_f32_e32 v1, 0x45800000, v0
	v_cndmask_b32_e32 v0, v0, v1, vcc
	v_lshl_add_u32 v1, v2, 2, v232
	ds_write_b32 v1, v0

.LBB0_738:
	s_andn2_b64 vcc, exec, s[0:1]
	s_cbranch_vccnz .LBB0_752
	v_readlane_b32 s0, v254, 45
	v_ashrrev_i32_e32 v4, 1, v198
	s_sub_i32 s8, s0, 64
	v_mad_i64_i32 v[0:1], s[0:1], v4, s16, 0
	s_and_b32 s0, s8, 0x7f
	v_mov_b32_e32 v2, 0xe8000
	v_and_b32_e32 v5, 1, v198
	v_mad_u64_u32 v[0:1], s[0:1], s0, v2, v[0:1]
	v_lshlrev_b32_e32 v192, 8, v5
	v_lshl_add_u64 v[0:1], v[0:1], 0, v[192:193]
	v_lshl_add_u64 v[0:1], s[52:53], 0, v[0:1]
	v_mov_b32_e32 v6, 0
	s_mov_b64 s[0:1], 0
	s_waitcnt lgkmcnt(0)
	s_barrier
	v_add_co_u32_e32 v2, vcc, 0x3dd0000, v0
	s_nop 1
	v_addc_co_u32_e32 v3, vcc, 0, v1, vcc
	global_load_dwordx4 v[64:67], v[2:3], off offset:2048
	global_load_dwordx4 v[68:71], v[2:3], off offset:2064
	global_load_dwordx4 v[72:75], v[2:3], off offset:2080
	global_load_dwordx4 v[76:79], v[2:3], off offset:2096
	global_load_dwordx4 v[80:83], v[2:3], off offset:2112
	global_load_dwordx4 v[84:87], v[2:3], off offset:2128
	global_load_dwordx4 v[88:91], v[2:3], off offset:2144
	global_load_dwordx4 v[92:95], v[2:3], off offset:2160
	global_load_dwordx4 v[96:99], v[2:3], off offset:2176
	global_load_dwordx4 v[100:103], v[2:3], off offset:2192
	global_load_dwordx4 v[104:107], v[2:3], off offset:2208
	global_load_dwordx4 v[108:111], v[2:3], off offset:2224
	global_load_dwordx4 v[112:115], v[2:3], off offset:2240
	global_load_dwordx4 v[116:119], v[2:3], off offset:2256
	global_load_dwordx4 v[120:123], v[2:3], off offset:2272
	global_load_dwordx4 v[124:127], v[2:3], off offset:2288
	s_waitcnt vmcnt(15)
	v_lshlrev_b32_e32 v8, 16, v64
	v_fmac_f32_e32 v6, v8, v8
	v_and_b32_e32 v8, 0xffff0000, v64
	v_lshlrev_b32_e32 v9, 16, v65
	v_pk_mul_f32 v[8:9], v[8:9], v[8:9]
	v_and_b32_e32 v10, 0xffff0000, v65
	v_lshlrev_b32_e32 v11, 16, v66
	v_pk_mul_f32 v[10:11], v[10:11], v[10:11]
	v_and_b32_e32 v12, 0xffff0000, v66
	v_lshlrev_b32_e32 v13, 16, v67
	v_pk_mul_f32 v[12:13], v[12:13], v[12:13]
	v_add_f32_e32 v6, v8, v6
	v_add_f32_e32 v6, v9, v6
	v_add_f32_e32 v6, v10, v6
	v_add_f32_e32 v6, v11, v6
	v_add_f32_e32 v6, v12, v6
	v_add_f32_e32 v6, v13, v6
	v_and_b32_e32 v8, 0xffff0000, v67
	v_fmac_f32_e32 v6, v8, v8
	s_waitcnt vmcnt(14)
	v_lshlrev_b32_e32 v8, 16, v68
	v_fmac_f32_e32 v6, v8, v8
	v_and_b32_e32 v8, 0xffff0000, v68
	v_lshlrev_b32_e32 v9, 16, v69
	v_pk_mul_f32 v[8:9], v[8:9], v[8:9]
	v_and_b32_e32 v10, 0xffff0000, v69
	v_lshlrev_b32_e32 v11, 16, v70
	v_pk_mul_f32 v[10:11], v[10:11], v[10:11]
	v_and_b32_e32 v12, 0xffff0000, v70
	v_lshlrev_b32_e32 v13, 16, v71
	v_pk_mul_f32 v[12:13], v[12:13], v[12:13]
	v_add_f32_e32 v6, v8, v6
	v_add_f32_e32 v6, v9, v6
	v_add_f32_e32 v6, v10, v6
	v_add_f32_e32 v6, v11, v6
	v_add_f32_e32 v6, v12, v6
	v_add_f32_e32 v6, v13, v6
	v_and_b32_e32 v8, 0xffff0000, v71
	v_fmac_f32_e32 v6, v8, v8
	s_waitcnt vmcnt(13)
	v_lshlrev_b32_e32 v8, 16, v72
	v_fmac_f32_e32 v6, v8, v8
	v_and_b32_e32 v8, 0xffff0000, v72
	v_lshlrev_b32_e32 v9, 16, v73
	v_pk_mul_f32 v[8:9], v[8:9], v[8:9]
	v_and_b32_e32 v10, 0xffff0000, v73
	v_lshlrev_b32_e32 v11, 16, v74
	v_pk_mul_f32 v[10:11], v[10:11], v[10:11]
	v_and_b32_e32 v12, 0xffff0000, v74
	v_lshlrev_b32_e32 v13, 16, v75
	v_pk_mul_f32 v[12:13], v[12:13], v[12:13]
	v_add_f32_e32 v6, v8, v6
	v_add_f32_e32 v6, v9, v6
	v_add_f32_e32 v6, v10, v6
	v_add_f32_e32 v6, v11, v6
	v_add_f32_e32 v6, v12, v6
	v_add_f32_e32 v6, v13, v6
	v_and_b32_e32 v8, 0xffff0000, v75
	v_fmac_f32_e32 v6, v8, v8
	s_waitcnt vmcnt(12)
	v_lshlrev_b32_e32 v8, 16, v76
	v_fmac_f32_e32 v6, v8, v8
	v_and_b32_e32 v8, 0xffff0000, v76
	v_lshlrev_b32_e32 v9, 16, v77
	v_pk_mul_f32 v[8:9], v[8:9], v[8:9]
	v_and_b32_e32 v10, 0xffff0000, v77
	v_lshlrev_b32_e32 v11, 16, v78
	v_pk_mul_f32 v[10:11], v[10:11], v[10:11]
	v_and_b32_e32 v12, 0xffff0000, v78
	v_lshlrev_b32_e32 v13, 16, v79
	v_pk_mul_f32 v[12:13], v[12:13], v[12:13]
	v_add_f32_e32 v6, v8, v6
	v_add_f32_e32 v6, v9, v6
	v_add_f32_e32 v6, v10, v6
	v_add_f32_e32 v6, v11, v6
	v_add_f32_e32 v6, v12, v6
	v_add_f32_e32 v6, v13, v6
	v_and_b32_e32 v8, 0xffff0000, v79
	v_fmac_f32_e32 v6, v8, v8
	s_waitcnt vmcnt(11)
	v_lshlrev_b32_e32 v8, 16, v80
	v_fmac_f32_e32 v6, v8, v8
	v_and_b32_e32 v8, 0xffff0000, v80
	v_lshlrev_b32_e32 v9, 16, v81
	v_pk_mul_f32 v[8:9], v[8:9], v[8:9]
	v_and_b32_e32 v10, 0xffff0000, v81
	v_lshlrev_b32_e32 v11, 16, v82
	v_pk_mul_f32 v[10:11], v[10:11], v[10:11]
	v_and_b32_e32 v12, 0xffff0000, v82
	v_lshlrev_b32_e32 v13, 16, v83
	v_pk_mul_f32 v[12:13], v[12:13], v[12:13]
	v_add_f32_e32 v6, v8, v6
	v_add_f32_e32 v6, v9, v6
	v_add_f32_e32 v6, v10, v6
	v_add_f32_e32 v6, v11, v6
	v_add_f32_e32 v6, v12, v6
	v_add_f32_e32 v6, v13, v6
	v_and_b32_e32 v8, 0xffff0000, v83
	v_fmac_f32_e32 v6, v8, v8
	s_waitcnt vmcnt(10)
	v_lshlrev_b32_e32 v8, 16, v84
	v_fmac_f32_e32 v6, v8, v8
	v_and_b32_e32 v8, 0xffff0000, v84
	v_lshlrev_b32_e32 v9, 16, v85
	v_pk_mul_f32 v[8:9], v[8:9], v[8:9]
	v_and_b32_e32 v10, 0xffff0000, v85
	v_lshlrev_b32_e32 v11, 16, v86
	v_pk_mul_f32 v[10:11], v[10:11], v[10:11]
	v_and_b32_e32 v12, 0xffff0000, v86
	v_lshlrev_b32_e32 v13, 16, v87
	v_pk_mul_f32 v[12:13], v[12:13], v[12:13]
	v_add_f32_e32 v6, v8, v6
	v_add_f32_e32 v6, v9, v6
	v_add_f32_e32 v6, v10, v6
	v_add_f32_e32 v6, v11, v6
	v_add_f32_e32 v6, v12, v6
	v_add_f32_e32 v6, v13, v6
	v_and_b32_e32 v8, 0xffff0000, v87
	v_fmac_f32_e32 v6, v8, v8
	s_waitcnt vmcnt(9)
	v_lshlrev_b32_e32 v8, 16, v88
	v_fmac_f32_e32 v6, v8, v8
	v_and_b32_e32 v8, 0xffff0000, v88
	v_lshlrev_b32_e32 v9, 16, v89
	v_pk_mul_f32 v[8:9], v[8:9], v[8:9]
	v_and_b32_e32 v10, 0xffff0000, v89
	v_lshlrev_b32_e32 v11, 16, v90
	v_pk_mul_f32 v[10:11], v[10:11], v[10:11]
	v_and_b32_e32 v12, 0xffff0000, v90
	v_lshlrev_b32_e32 v13, 16, v91
	v_pk_mul_f32 v[12:13], v[12:13], v[12:13]
	v_add_f32_e32 v6, v8, v6
	v_add_f32_e32 v6, v9, v6
	v_add_f32_e32 v6, v10, v6
	v_add_f32_e32 v6, v11, v6
	v_add_f32_e32 v6, v12, v6
	v_add_f32_e32 v6, v13, v6
	v_and_b32_e32 v8, 0xffff0000, v91
	v_fmac_f32_e32 v6, v8, v8
	s_waitcnt vmcnt(8)
	v_lshlrev_b32_e32 v8, 16, v92
	v_fmac_f32_e32 v6, v8, v8
	v_and_b32_e32 v8, 0xffff0000, v92
	v_lshlrev_b32_e32 v9, 16, v93
	v_pk_mul_f32 v[8:9], v[8:9], v[8:9]
	v_and_b32_e32 v10, 0xffff0000, v93
	v_lshlrev_b32_e32 v11, 16, v94
	v_pk_mul_f32 v[10:11], v[10:11], v[10:11]
	v_and_b32_e32 v12, 0xffff0000, v94
	v_lshlrev_b32_e32 v13, 16, v95
	v_pk_mul_f32 v[12:13], v[12:13], v[12:13]
	v_add_f32_e32 v6, v8, v6
	v_add_f32_e32 v6, v9, v6
	v_add_f32_e32 v6, v10, v6
	v_add_f32_e32 v6, v11, v6
	v_add_f32_e32 v6, v12, v6
	v_add_f32_e32 v6, v13, v6
	v_and_b32_e32 v8, 0xffff0000, v95
	v_fmac_f32_e32 v6, v8, v8
	s_waitcnt vmcnt(7)
	v_lshlrev_b32_e32 v8, 16, v96
	v_fmac_f32_e32 v6, v8, v8
	v_and_b32_e32 v8, 0xffff0000, v96
	v_lshlrev_b32_e32 v9, 16, v97
	v_pk_mul_f32 v[8:9], v[8:9], v[8:9]
	v_and_b32_e32 v10, 0xffff0000, v97
	v_lshlrev_b32_e32 v11, 16, v98
	v_pk_mul_f32 v[10:11], v[10:11], v[10:11]
	v_and_b32_e32 v12, 0xffff0000, v98
	v_lshlrev_b32_e32 v13, 16, v99
	v_pk_mul_f32 v[12:13], v[12:13], v[12:13]
	v_add_f32_e32 v6, v8, v6
	v_add_f32_e32 v6, v9, v6
	v_add_f32_e32 v6, v10, v6
	v_add_f32_e32 v6, v11, v6
	v_add_f32_e32 v6, v12, v6
	v_add_f32_e32 v6, v13, v6
	v_and_b32_e32 v8, 0xffff0000, v99
	v_fmac_f32_e32 v6, v8, v8
	s_waitcnt vmcnt(6)
	v_lshlrev_b32_e32 v8, 16, v100
	v_fmac_f32_e32 v6, v8, v8
	v_and_b32_e32 v8, 0xffff0000, v100
	v_lshlrev_b32_e32 v9, 16, v101
	v_pk_mul_f32 v[8:9], v[8:9], v[8:9]
	v_and_b32_e32 v10, 0xffff0000, v101
	v_lshlrev_b32_e32 v11, 16, v102
	v_pk_mul_f32 v[10:11], v[10:11], v[10:11]
	v_and_b32_e32 v12, 0xffff0000, v102
	v_lshlrev_b32_e32 v13, 16, v103
	v_pk_mul_f32 v[12:13], v[12:13], v[12:13]
	v_add_f32_e32 v6, v8, v6
	v_add_f32_e32 v6, v9, v6
	v_add_f32_e32 v6, v10, v6
	v_add_f32_e32 v6, v11, v6
	v_add_f32_e32 v6, v12, v6
	v_add_f32_e32 v6, v13, v6
	v_and_b32_e32 v8, 0xffff0000, v103
	v_fmac_f32_e32 v6, v8, v8
	s_waitcnt vmcnt(5)
	v_lshlrev_b32_e32 v8, 16, v104
	v_fmac_f32_e32 v6, v8, v8
	v_and_b32_e32 v8, 0xffff0000, v104
	v_lshlrev_b32_e32 v9, 16, v105
	v_pk_mul_f32 v[8:9], v[8:9], v[8:9]
	v_and_b32_e32 v10, 0xffff0000, v105
	v_lshlrev_b32_e32 v11, 16, v106
	v_pk_mul_f32 v[10:11], v[10:11], v[10:11]
	v_and_b32_e32 v12, 0xffff0000, v106
	v_lshlrev_b32_e32 v13, 16, v107
	v_pk_mul_f32 v[12:13], v[12:13], v[12:13]
	v_add_f32_e32 v6, v8, v6
	v_add_f32_e32 v6, v9, v6
	v_add_f32_e32 v6, v10, v6
	v_add_f32_e32 v6, v11, v6
	v_add_f32_e32 v6, v12, v6
	v_add_f32_e32 v6, v13, v6
	v_and_b32_e32 v8, 0xffff0000, v107
	v_fmac_f32_e32 v6, v8, v8
	s_waitcnt vmcnt(4)
	v_lshlrev_b32_e32 v8, 16, v108
	v_fmac_f32_e32 v6, v8, v8
	v_and_b32_e32 v8, 0xffff0000, v108
	v_lshlrev_b32_e32 v9, 16, v109
	v_pk_mul_f32 v[8:9], v[8:9], v[8:9]
	v_and_b32_e32 v10, 0xffff0000, v109
	v_lshlrev_b32_e32 v11, 16, v110
	v_pk_mul_f32 v[10:11], v[10:11], v[10:11]
	v_and_b32_e32 v12, 0xffff0000, v110
	v_lshlrev_b32_e32 v13, 16, v111
	v_pk_mul_f32 v[12:13], v[12:13], v[12:13]
	v_add_f32_e32 v6, v8, v6
	v_add_f32_e32 v6, v9, v6
	v_add_f32_e32 v6, v10, v6
	v_add_f32_e32 v6, v11, v6
	v_add_f32_e32 v6, v12, v6
	v_add_f32_e32 v6, v13, v6
	v_and_b32_e32 v8, 0xffff0000, v111
	v_fmac_f32_e32 v6, v8, v8
	s_waitcnt vmcnt(3)
	v_lshlrev_b32_e32 v8, 16, v112
	v_fmac_f32_e32 v6, v8, v8
	v_and_b32_e32 v8, 0xffff0000, v112
	v_lshlrev_b32_e32 v9, 16, v113
	v_pk_mul_f32 v[8:9], v[8:9], v[8:9]
	v_and_b32_e32 v10, 0xffff0000, v113
	v_lshlrev_b32_e32 v11, 16, v114
	v_pk_mul_f32 v[10:11], v[10:11], v[10:11]
	v_and_b32_e32 v12, 0xffff0000, v114
	v_lshlrev_b32_e32 v13, 16, v115
	v_pk_mul_f32 v[12:13], v[12:13], v[12:13]
	v_add_f32_e32 v6, v8, v6
	v_add_f32_e32 v6, v9, v6
	v_add_f32_e32 v6, v10, v6
	v_add_f32_e32 v6, v11, v6
	v_add_f32_e32 v6, v12, v6
	v_add_f32_e32 v6, v13, v6
	v_and_b32_e32 v8, 0xffff0000, v115
	v_fmac_f32_e32 v6, v8, v8
	s_waitcnt vmcnt(2)
	v_lshlrev_b32_e32 v8, 16, v116
	v_fmac_f32_e32 v6, v8, v8
	v_and_b32_e32 v8, 0xffff0000, v116
	v_lshlrev_b32_e32 v9, 16, v117
	v_pk_mul_f32 v[8:9], v[8:9], v[8:9]
	v_and_b32_e32 v10, 0xffff0000, v117
	v_lshlrev_b32_e32 v11, 16, v118
	v_pk_mul_f32 v[10:11], v[10:11], v[10:11]
	v_and_b32_e32 v12, 0xffff0000, v118
	v_lshlrev_b32_e32 v13, 16, v119
	v_pk_mul_f32 v[12:13], v[12:13], v[12:13]
	v_add_f32_e32 v6, v8, v6
	v_add_f32_e32 v6, v9, v6
	v_add_f32_e32 v6, v10, v6
	v_add_f32_e32 v6, v11, v6
	v_add_f32_e32 v6, v12, v6
	v_add_f32_e32 v6, v13, v6
	v_and_b32_e32 v8, 0xffff0000, v119
	v_fmac_f32_e32 v6, v8, v8
	s_waitcnt vmcnt(1)
	v_lshlrev_b32_e32 v8, 16, v120
	v_fmac_f32_e32 v6, v8, v8
	v_and_b32_e32 v8, 0xffff0000, v120
	v_lshlrev_b32_e32 v9, 16, v121
	v_pk_mul_f32 v[8:9], v[8:9], v[8:9]
	v_and_b32_e32 v10, 0xffff0000, v121
	v_lshlrev_b32_e32 v11, 16, v122
	v_pk_mul_f32 v[10:11], v[10:11], v[10:11]
	v_and_b32_e32 v12, 0xffff0000, v122
	v_lshlrev_b32_e32 v13, 16, v123
	v_pk_mul_f32 v[12:13], v[12:13], v[12:13]
	v_add_f32_e32 v6, v8, v6
	v_add_f32_e32 v6, v9, v6
	v_add_f32_e32 v6, v10, v6
	v_add_f32_e32 v6, v11, v6
	v_add_f32_e32 v6, v12, v6
	v_add_f32_e32 v6, v13, v6
	v_and_b32_e32 v8, 0xffff0000, v123
	v_fmac_f32_e32 v6, v8, v8
	s_waitcnt vmcnt(0)
	v_lshlrev_b32_e32 v8, 16, v124
	v_fmac_f32_e32 v6, v8, v8
	v_and_b32_e32 v8, 0xffff0000, v124
	v_lshlrev_b32_e32 v9, 16, v125
	v_pk_mul_f32 v[8:9], v[8:9], v[8:9]
	v_and_b32_e32 v10, 0xffff0000, v125
	v_lshlrev_b32_e32 v11, 16, v126
	v_pk_mul_f32 v[10:11], v[10:11], v[10:11]
	v_and_b32_e32 v12, 0xffff0000, v126
	v_lshlrev_b32_e32 v13, 16, v127
	v_pk_mul_f32 v[12:13], v[12:13], v[12:13]
	v_add_f32_e32 v6, v8, v6
	v_add_f32_e32 v6, v9, v6
	v_add_f32_e32 v6, v10, v6
	v_add_f32_e32 v6, v11, v6
	v_add_f32_e32 v6, v12, v6
	v_add_f32_e32 v6, v13, v6
	v_and_b32_e32 v8, 0xffff0000, v127
	v_fmac_f32_e32 v6, v8, v8
	v_and_b32_e32 v1, 64, v225
	v_xor_b32_e32 v0, 1, v225
	v_add_u32_e32 v1, 64, v1
	v_cmp_lt_i32_e32 vcc, v0, v1
	s_nop 1
	v_cndmask_b32_e32 v0, v225, v0, vcc
	v_lshlrev_b32_e32 v0, 2, v0
	ds_bpermute_b32 v0, v0, v6
	v_cmp_eq_u32_e32 vcc, 0, v5
	s_and_saveexec_b64 s[0:1], vcc
	s_movk_i32 s12, 0x90
	s_cbranch_execz .LBB0_743
	s_waitcnt lgkmcnt(0)
	v_add_f32_e32 v0, v6, v0
	v_fmamk_f32 v0, v0, 0x3b800000, v224
	s_mov_b32 s9, 0x800000
	v_mul_f32_e32 v1, 0x4b800000, v0
	v_cmp_gt_f32_e32 vcc, s9, v0
	s_nop 1
	v_cndmask_b32_e32 v0, v0, v1, vcc
	v_rsq_f32_e32 v0, v0
	s_nop 0
	v_mul_f32_e32 v1, 0x45800000, v0
	v_cndmask_b32_e32 v0, v0, v1, vcc
	v_lshl_add_u32 v1, v4, 2, v232
	ds_write_b32 v1, v0
